# per-segment priority also in the MLA attention tile loop
# speedup vs baseline: 1.0196x; 1.0022x over previous
; DI f32x16 mfma32(bf16x8 a, bf16x8 b, f32x16 c) { return __builtin_amdgcn_mfma_f32_32x32x16_bf16(a, b, c, 0, 0, 0); }
; DI int crow(int reg, int h) { return (reg & 3) + 8 * (reg >> 2) + 4 * h; }
; template <int DQK, int DV, int KW0, int MODE> ...
;     ...
;     {
;       bf16x8 kfa[DQK / 16], kfb[DQK / 16], qv[DQK / 16];
; #pragma unroll
;       for (int kk = 0; kk < DQK / 16; ++kk) {
;         kfa[kk] = *(const bf16x8*)(cur + r * (KS * 2) + kk * 32 + h * 16);
;         kfb[kk] = *(const bf16x8*)(cur + (32 + r) * (KS * 2) + kk * 32 + h * 16);
;         qv[kk] = QLDS ? *(const bf16x8*)(qbase + kk * 1024) : qf[kk];
;       }
; #pragma unroll
;       for (int kk = 0; kk < DQK / 16; ++kk) {
;         S0 = mfma32(kfa[kk], qv[kk], S0);
;         S1 = mfma32(kfb[kk], qv[kk], S1);
;       }
;       __builtin_amdgcn_sched_group_barrier(0x100, (QLDS ? 3 : 2) * (DQK / 16), 0);
;       __builtin_amdgcn_sched_group_barrier(0x008, 2 * (DQK / 16), 0);
;     }
;     if (MODE == 2) {
;       if (it >= 4) {
;         const int w = wlo + it - 4;
;         if (w < 2 || w > 3) {
;           const int kpos0 = (qn - 1) * 128 + 64 * w, qpos = qn * 128 + wid * 32 + r;
; #pragma unroll
;           for (int e = 0; e < 16; ++e) {
;             const int d0 = qpos - (kpos0 + crow(e, h)), d1 = d0 - 32;
;             if (d0 > 128 || d0 < -128) S0[e] = -1e30f;
;             if (d1 > 128 || d1 < -128) S1[e] = -1e30f;
;           }
;         }
;       }
;     }
;     float mx = S0[0];
; #pragma unroll
;     for (int e = 1; e < 16; ++e) mx = fmaxf(mx, S0[e]);
; #pragma unroll
;     for (int e = 0; e < 16; ++e) mx = fmaxf(mx, S1[e]);
;     mx = fmaxf(mx, __shfl_xor(mx, 32));
;     const float mn = fmaxf(m, mx);
;     const bool grow = __builtin_amdgcn_ballot_w64(mx > m) != 0ull;
;     const float alpha = __builtin_amdgcn_exp2f((m - mn) * c);
;     m = mn;
;     const float mc = mn * c;
;     float ps = 0.f;
; #pragma unroll
;     for (int e = 0; e < 16; ++e) { S0[e] = __builtin_amdgcn_exp2f(S0[e] * c - mc); ps += S0[e]; }
; #pragma unroll
;     for (int e = 0; e < 16; ++e) { S1[e] = __builtin_amdgcn_exp2f(S1[e] * c - mc); ps += S1[e]; }
;     if (grow) {
;       l *= alpha;
; #pragma unroll
;       for (int t = 0; t < DV / 32; ++t)
; #pragma unroll
;         for (int e = 0; e < 16; ++e) O[t][e] *= alpha;
;     }
.LBB0_134:
	s_bitcmp1_b32 s46, 0
	s_cselect_b32 s10, 0x6400, 0
	s_add_i32 s15, s10, 16
	v_add3_u32 v50, s15, v164, v165
	ds_read_b128 v[38:41], v50
	ds_read_b128 v[42:45], v50 offset:32
	ds_read_b128 v[34:37], v50 offset:6656
	ds_read_b128 v[176:179], v50 offset:6688
	ds_read_b128 v[46:49], v50 offset:64
	ds_read_b128 v[180:183], v50 offset:6720
	ds_read_b128 v[192:195], v50 offset:96
	ds_read_b128 v[218:221], v50 offset:6752
	ds_read_b128 v[222:225], v50 offset:128
	ds_read_b128 v[226:229], v50 offset:6784
	ds_read_b128 v[230:233], v50 offset:160
	ds_read_b128 v[234:237], v50 offset:6816
	s_setprio 1
	s_waitcnt lgkmcnt(11)
	v_mfma_f32_32x32x16_bf16 v[50:65], v[38:41], v[66:69], 0
	s_waitcnt lgkmcnt(10)
	v_mfma_f32_32x32x16_bf16 v[50:65], v[42:45], v[70:73], v[50:65]
	s_waitcnt lgkmcnt(7)
	v_mfma_f32_32x32x16_bf16 v[50:65], v[46:49], v[74:77], v[50:65]
	v_mfma_f32_32x32x16_bf16 v[34:49], v[34:37], v[66:69], 0
	v_mfma_f32_32x32x16_bf16 v[34:49], v[176:179], v[70:73], v[34:49]
	s_waitcnt lgkmcnt(5)
	v_mfma_f32_32x32x16_bf16 v[50:65], v[192:195], v[78:81], v[50:65]
	v_mfma_f32_32x32x16_bf16 v[34:49], v[180:183], v[74:77], v[34:49]
	s_waitcnt lgkmcnt(3)
	v_mfma_f32_32x32x16_bf16 v[50:65], v[222:225], v[82:85], v[50:65]
	v_mfma_f32_32x32x16_bf16 v[34:49], v[218:221], v[78:81], v[34:49]
	s_waitcnt lgkmcnt(1)
	v_mfma_f32_32x32x16_bf16 v[50:65], v[230:233], v[86:89], v[50:65]
	v_mfma_f32_32x32x16_bf16 v[34:49], v[226:229], v[82:85], v[34:49]
	s_nop 10
	v_max_f32_e32 v148, v51, v51
	v_max_f32_e32 v150, v50, v50
	v_max_f32_e32 v148, v150, v148
	v_max3_f32 v148, v148, v52, v53
	v_max3_f32 v148, v148, v54, v55
	v_max3_f32 v148, v148, v56, v57
	v_max3_f32 v148, v148, v58, v59
	s_waitcnt lgkmcnt(0)
	v_mfma_f32_32x32x16_bf16 v[34:49], v[234:237], v[86:89], v[34:49]
	s_setprio 0
	v_max3_f32 v148, v148, v60, v61
	v_max3_f32 v148, v148, v62, v63
	v_max3_f32 v148, v148, v64, v65
	s_nop 8
	v_max3_f32 v148, v148, v34, v35
	v_max3_f32 v148, v148, v36, v37
	v_max3_f32 v148, v148, v38, v39
	v_max3_f32 v148, v148, v40, v41
	v_max3_f32 v148, v148, v42, v43
	v_max3_f32 v148, v148, v44, v45
	v_max3_f32 v148, v148, v46, v47
	v_max3_f32 v148, v148, v48, v49
	ds_bpermute_b32 v150, v166, v148
	s_waitcnt lgkmcnt(0)
	v_max_f32_e32 v150, v150, v150
	v_max_f32_e32 v148, v148, v150
	v_max_f32_e32 v150, v149, v149
	v_max_f32_e32 v151, v150, v148
	v_cmp_gt_f32_e32 vcc, v148, v149
	s_cbranch_vccz .LBB0_136
	v_sub_f32_e32 v148, v149, v151
	v_mul_f32_e32 v148, 0x3e16c740, v148
	v_exp_f32_e32 v148, v148
	s_nop 0
	v_pk_mul_f32 v[32:33], v[32:33], v[148:149] op_sel_hi:[1,0]
	v_pk_mul_f32 v[30:31], v[30:31], v[148:149] op_sel_hi:[1,0]
	v_pk_mul_f32 v[28:29], v[28:29], v[148:149] op_sel_hi:[1,0]
	v_pk_mul_f32 v[26:27], v[26:27], v[148:149] op_sel_hi:[1,0]
	v_pk_mul_f32 v[24:25], v[24:25], v[148:149] op_sel_hi:[1,0]
	v_pk_mul_f32 v[22:23], v[22:23], v[148:149] op_sel_hi:[1,0]
	v_pk_mul_f32 v[20:21], v[20:21], v[148:149] op_sel_hi:[1,0]
	v_pk_mul_f32 v[18:19], v[18:19], v[148:149] op_sel_hi:[1,0]
	v_pk_mul_f32 v[16:17], v[16:17], v[148:149] op_sel_hi:[1,0]
	v_pk_mul_f32 v[14:15], v[14:15], v[148:149] op_sel_hi:[1,0]
	v_pk_mul_f32 v[12:13], v[12:13], v[148:149] op_sel_hi:[1,0]
	v_pk_mul_f32 v[10:11], v[10:11], v[148:149] op_sel_hi:[1,0]
	v_pk_mul_f32 v[8:9], v[8:9], v[148:149] op_sel_hi:[1,0]
	v_pk_mul_f32 v[6:7], v[6:7], v[148:149] op_sel_hi:[1,0]
	v_pk_mul_f32 v[4:5], v[4:5], v[148:149] op_sel_hi:[1,0]
	v_pk_mul_f32 v[2:3], v[2:3], v[148:149] op_sel_hi:[1,0]
	v_mul_f32_e32 v113, v113, v148
; DI unsigned pk2(float a, float b) { f32x2 v = {a, b}; bf2_t r = __builtin_convertvector(v, bf2_t); return __builtin_bit_cast(unsigned, r); }
; #define PV_TILE64_(T) do { TRV8_192_T##T(R, vaddr); \
;           _Pragma("unroll") for (int st = 0; st < 2; ++st) _Pragma("unroll") for (int s = 0; s < 2; ++s) { const int ix = (st * 2 + s) * 2; \
;             const bf16x8 va = __builtin_shufflevector(R[ix], R[ix + 1], 0, 1, 2, 3, 4, 5, 6, 7); O[T] = mfma32(va, pf[st][s], O[T]); } } while (0)
; template <int DQK, int DV, int KW0, int MODE> ...
;     ...
;     const float mc = mn * c;
;     float ps = 0.f;
; #pragma unroll
;     for (int e = 0; e < 16; ++e) { S0[e] = __builtin_amdgcn_exp2f(S0[e] * c - mc); ps += S0[e]; }
; #pragma unroll
;     for (int e = 0; e < 16; ++e) { S1[e] = __builtin_amdgcn_exp2f(S1[e] * c - mc); ps += S1[e]; }
;     if (grow) {
;       l *= alpha;
; #pragma unroll
;       for (int t = 0; t < DV / 32; ++t)
; #pragma unroll
;         for (int e = 0; e < 16; ++e) O[t][e] *= alpha;
;     }
;     l += ps;
;     bf16x8 pf[2][2];
; #pragma unroll
;     for (int s = 0; s < 2; ++s) {
;       u32x4 w0, w1;
;       w0.x = pk2(S0[8 * s + 0], S0[8 * s + 1]); w0.y = pk2(S0[8 * s + 2], S0[8 * s + 3]); w0.z = pk2(S0[8 * s + 4], S0[8 * s + 5]); w0.w = pk2(S0[8 * s + 6], S0[8 * s + 7]);
;       w1.x = pk2(S1[8 * s + 0], S1[8 * s + 1]); w1.y = pk2(S1[8 * s + 2], S1[8 * s + 3]); w1.z = pk2(S1[8 * s + 4], S1[8 * s + 5]); w1.w = pk2(S1[8 * s + 6], S1[8 * s + 7]);
;       pf[0][s] = __builtin_bit_cast(bf16x8, w0); pf[1][s] = __builtin_bit_cast(bf16x8, w1);
;     }
;     {
;       const unsigned vaddr = (unsigned)(size_t)(cur + KB) + (unsigned)((4 * h + ((lane & 15) >> 2)) * VSB + ((lane >> 4) & 1) * 32 + (lane & 3) * 8);
;       if (DV == 64) {
;         s16x4 R[8];
;     ...
;         PV_TILE64_(0); PV_TILE64_(1);
;     ...
;       } else {
;         s16x4 R[8];
;     ...
;         PV_TILE_(0); PV_TILE_(1); PV_TILE_(2); PV_TILE_(3);
;     ...
;       }
;     }
;     if (DV > 64) { __builtin_amdgcn_sched_barrier(0); if (more) attn_gload<DQK, DV, KW0, 3>(kreg, vreg, k0p, ldk0, k1p, ldk1, vp, ldv, key_tile_row<MODE>(it + 1, b, qn, wlo), tid); }
;     if (more) attn_sstore<DQK, DV>(kreg, vreg, smem + ((it + 1) & 1) * STG, tid);
.LBB0_136:
	v_mov_b32_e32 v150, v65
	v_pk_mul_f32 v[148:149], v[150:151], s[30:31] op_sel_hi:[1,0]
	s_addk_i32 s15, 0x3400
	v_fma_f32 v50, v50, s30, -v149
	v_fma_f32 v51, v51, s30, -v149
	v_fma_f32 v52, v52, s30, -v149
	v_fma_f32 v53, v53, s30, -v149
	v_fma_f32 v54, v54, s30, -v149
	v_fma_f32 v55, v55, s30, -v149
	v_fma_f32 v56, v56, s30, -v149
	v_fma_f32 v57, v57, s30, -v149
	v_exp_f32_e32 v50, v50
	v_exp_f32_e32 v51, v51
	v_exp_f32_e32 v52, v52
	v_exp_f32_e32 v53, v53
	v_exp_f32_e32 v54, v54
	v_exp_f32_e32 v55, v55
	v_exp_f32_e32 v56, v56
	v_exp_f32_e32 v57, v57
	v_cvt_pk_bf16_f32 v176, v50, v51
	v_cvt_pk_bf16_f32 v177, v52, v53
	v_cvt_pk_bf16_f32 v178, v54, v55
	v_cvt_pk_bf16_f32 v179, v56, v57
	v_sub_f32_e32 v65, v148, v149
	v_add_u32_e32 v148, s15, v167
	s_setprio 1
	ds_read_b64_tr_b16 v[234:235], v148 offset:0
	ds_read_b64_tr_b16 v[236:237], v148 offset:1536
	ds_read_b64_tr_b16 v[230:231], v148 offset:3072
	ds_read_b64_tr_b16 v[232:233], v148 offset:4608
	ds_read_b64_tr_b16 v[226:227], v148 offset:6144
	ds_read_b64_tr_b16 v[228:229], v148 offset:7680
	ds_read_b64_tr_b16 v[222:223], v148 offset:9216
	ds_read_b64_tr_b16 v[224:225], v148 offset:10752
	s_waitcnt lgkmcnt(0)
	v_fma_f32 v58, v58, s30, -v149
	v_mfma_f32_32x32x16_bf16 v[2:17], v[234:237], v[176:179], v[2:17]
	v_fma_f32 v59, v59, s30, -v149
	v_fma_f32 v60, v60, s30, -v149
	v_fma_f32 v61, v61, s30, -v149
	v_fma_f32 v62, v62, s30, -v149
	v_fma_f32 v63, v63, s30, -v149
	v_fma_f32 v64, v64, s30, -v149
	v_exp_f32_e32 v58, v58
	v_exp_f32_e32 v59, v59
	v_exp_f32_e32 v60, v60
	v_exp_f32_e32 v61, v61
	v_exp_f32_e32 v62, v62
	v_exp_f32_e32 v63, v63
	v_exp_f32_e32 v64, v64
	v_exp_f32_e32 v65, v65
	v_cvt_pk_bf16_f32 v192, v58, v59
	v_cvt_pk_bf16_f32 v193, v60, v61
	v_cvt_pk_bf16_f32 v194, v62, v63
	v_cvt_pk_bf16_f32 v195, v64, v65
	v_fma_f32 v34, v34, s30, -v149
	v_fma_f32 v35, v35, s30, -v149
	v_mfma_f32_32x32x16_bf16 v[2:17], v[230:233], v[192:195], v[2:17]
	v_fma_f32 v36, v36, s30, -v149
	v_fma_f32 v37, v37, s30, -v149
	v_fma_f32 v38, v38, s30, -v149
	v_fma_f32 v39, v39, s30, -v149
	v_fma_f32 v40, v40, s30, -v149
	v_fma_f32 v41, v41, s30, -v149
	v_exp_f32_e32 v34, v34
	v_exp_f32_e32 v35, v35
	v_exp_f32_e32 v36, v36
	v_exp_f32_e32 v37, v37
	v_exp_f32_e32 v38, v38
	v_exp_f32_e32 v39, v39
	v_exp_f32_e32 v40, v40
	v_exp_f32_e32 v41, v41
	v_cvt_pk_bf16_f32 v180, v34, v35
	v_cvt_pk_bf16_f32 v181, v36, v37
	v_cvt_pk_bf16_f32 v182, v38, v39
	v_cvt_pk_bf16_f32 v183, v40, v41
	v_fma_f32 v42, v42, s30, -v149
	v_fma_f32 v43, v43, s30, -v149
	v_mfma_f32_32x32x16_bf16 v[2:17], v[226:229], v[180:183], v[2:17]
	v_fma_f32 v44, v44, s30, -v149
	v_fma_f32 v45, v45, s30, -v149
	v_fma_f32 v46, v46, s30, -v149
	v_fma_f32 v47, v47, s30, -v149
	v_fma_f32 v48, v48, s30, -v149
	v_fma_f32 v49, v49, s30, -v149
	v_exp_f32_e32 v42, v42
	v_exp_f32_e32 v43, v43
	v_exp_f32_e32 v44, v44
	v_exp_f32_e32 v45, v45
	v_exp_f32_e32 v46, v46
	v_exp_f32_e32 v47, v47
	v_exp_f32_e32 v48, v48
	v_exp_f32_e32 v49, v49
	v_cvt_pk_bf16_f32 v218, v42, v43
	v_cvt_pk_bf16_f32 v219, v44, v45
	v_cvt_pk_bf16_f32 v220, v46, v47
	v_cvt_pk_bf16_f32 v221, v48, v49
	s_andn2_b64 vcc, exec, s[16:17]
	s_nop 0
	v_mfma_f32_32x32x16_bf16 v[2:17], v[222:225], v[218:221], v[2:17]
	ds_read_b64_tr_b16 v[234:235], v148 offset:64
	ds_read_b64_tr_b16 v[236:237], v148 offset:1600
	ds_read_b64_tr_b16 v[230:231], v148 offset:3136
	ds_read_b64_tr_b16 v[232:233], v148 offset:4672
	ds_read_b64_tr_b16 v[226:227], v148 offset:6208
	ds_read_b64_tr_b16 v[228:229], v148 offset:7744
	ds_read_b64_tr_b16 v[222:223], v148 offset:9280
	ds_read_b64_tr_b16 v[224:225], v148 offset:10816
	s_waitcnt lgkmcnt(0)
	s_nop 0
	v_mfma_f32_32x32x16_bf16 v[18:33], v[234:237], v[176:179], v[18:33]
	v_mfma_f32_32x32x16_bf16 v[18:33], v[230:233], v[192:195], v[18:33]
	v_mfma_f32_32x32x16_bf16 v[18:33], v[226:229], v[180:183], v[18:33]
	v_mfma_f32_32x32x16_bf16 v[18:33], v[222:225], v[218:221], v[18:33]
	s_setprio 0
	s_cbranch_vccnz .LBB0_138
	s_bitcmp1_b32 s29, 0
	s_cselect_b32 s10, 0x6400, 0
	s_add_i32 s10, s10, 16
	v_add3_u32 v148, s10, v156, v157
	s_waitcnt vmcnt(4)
	ds_write_b128 v148, v[90:93]
	v_add3_u32 v148, s10, v158, v159
	s_waitcnt vmcnt(3)
	ds_write_b128 v148, v[94:97]
	v_add3_u32 v148, s10, v160, v161
	s_waitcnt vmcnt(2)
	ds_write_b128 v148, v[98:101]
	v_add3_u32 v148, s10, v163, v155
	s_waitcnt vmcnt(1)
	ds_write_b128 v148, v[102:105] offset:13312
	s_waitcnt vmcnt(0)
	ds_write_b128 v148, v[106:109] offset:13504
